# attention phase: one static s_setprio 1 for waves 4-7 (reset at the phase end)
# baseline (speedup 1.0000x reference)
; #define LAS __attribute__((address_space(3)))
; __device__ __forceinline__ void attn_phase(const bf16_t* Q, const bf16_t* KF, const bf16_t* V, bf16_t* VT, bf16_t* O, LAS unsigned char* lds, unsigned* ctr) {
;     const int tid__ = otid(); const int lane = tid__ & 63, wave = tid__ >> 6, c32 = lane & 31, hf = lane >> 5;
;     for (int bh = blockIdx.x; bh < 256; bh += gridDim.x) {
;         const int b = bh >> 4, h = bh & 15;
;         bf16_t* vtw = VT + (size_t)(b * 16 + h) * 64 * SEQ;
;         __syncthreads();
;         if (tid__ == 0) *ctr = 0u;
;         const bf16_t* kfw = KF + (size_t)(b * 16 + h) * 64 * SEQ;
;         {
;             LAS bf16_t* scr = (LAS bf16_t*)(lds + wave * 8704);
;             for (int st = wave * 4; st < wave * 4 + 4; ++st) {
;                 const int s0 = st * 64;
; #pragma unroll
;                 for (int j = 0; j < 8; ++j) { const int i = (lane >> 3) + 8 * j, c = lane & 7;
;                     const u32x4 w = *(const u32x4*)(V + (size_t)(b * SEQ + s0 + i) * D + h * 64 + 8 * c);
;                     *(LAS u32x2*)(scr + i * 68 + 8 * c) = (u32x2){w.x, w.y}; *(LAS u32x2*)(scr + i * 68 + 8 * c + 4) = (u32x2){w.z, w.w}; }
;                 asm volatile("s_waitcnt lgkmcnt(0)" ::: "memory");
; #pragma unroll
;                 for (int blk = 0; blk < 8; ++blk) { const int t32 = blk >> 2, db = (blk >> 1) & 1, ks = blk & 1;
;                     unsigned short e[8];
; #pragma unroll
;                     for (int k = 0; k < 8; ++k) e[k] = scr[(32 * t32 + 16 * ks + 8 * (k >> 2) + 4 * hf + (k & 3)) * 68 + db * 32 + c32];
;                     u32x4 w; w.x = e[0] | ((unsigned)e[1] << 16); w.y = e[2] | ((unsigned)e[3] << 16); w.z = e[4] | ((unsigned)e[5] << 16); w.w = e[6] | ((unsigned)e[7] << 16);
;                     *(u32x4*)(vtw + (size_t)((((st * 2 + t32) * 2 + db) * 2 + ks) * 64 + lane) * 8) = w; }
;                 asm volatile("s_waitcnt lgkmcnt(0)" ::: "memory");
;             }
;             asm volatile("s_waitcnt vmcnt(0)" ::: "memory"); __syncthreads();
;         }
;         const bf16_t* vtb = vtw;
;         for (;;) {
;             unsigned uq = 0u;
;             if (lane == 0) uq = atomicAdd(ctr, 1u);
;             uq = (unsigned)__builtin_amdgcn_readfirstlane((int)uq);
;             if (uq >= 64u) break;
;             const int qb = 63 - (int)uq, t0 = qb * 32;
;             bf16x8 qf[4];
; #pragma unroll
.LBB0_1735:
	s_or_b64 exec, exec, s[10:11]
	s_mov_b32 s98, 0x42a00000
	v_readfirstlane_b32 s99, v219
	s_nop 3
	s_lshr_b32 s99, s99, 6
	s_cmp_ge_u32 s99, 4
	s_cbranch_scc0 .Lattn_prio_done
	s_setprio 1
.Lattn_prio_done:
	s_waitcnt lgkmcnt(0)
	v_mov_b32_e32 v0, v219
	s_andn2_b64 vcc, exec, s[20:21]
	s_barrier
	s_cbranch_vccnz .LBB0_1753
	v_ashrrev_i32_e32 v2, 6, v0
	s_movk_i32 s6, 0x2200
	v_and_b32_e32 v1, 63, v0
	v_and_b32_e32 v84, 31, v0
	v_cmp_eq_u32_e64 s[10:11], 0, v0
	v_mul_lo_u32 v3, v2, s6
	v_bfe_u32 v4, v0, 3, 3
	v_lshlrev_b32_e32 v5, 4, v0
	v_lshrrev_b32_e32 v0, 3, v0
	v_add_u32_e32 v3, 0, v3
	v_and_b32_e32 v64, 0x70, v5
	v_mov_b32_e32 v65, 0
	v_and_b32_e32 v0, 4, v0
	v_lshl_add_u64 v[66:67], s[18:19], 0, v[64:65]
	v_add_u32_e32 v5, v3, v64
	v_lshlrev_b32_e32 v64, 1, v0
	v_mul_u32_u24_e32 v6, 0x88, v0
	v_mul_u32_u24_e32 v7, 0x88, v4
	v_or_b32_e32 v8, 1, v0
	v_or_b32_e32 v9, 2, v0
	v_or_b32_e32 v10, 3, v0
	v_or_b32_e32 v11, 8, v0
	v_or_b32_e32 v12, 9, v0
	v_or_b32_e32 v13, 10, v0
	v_or_b32_e32 v14, 11, v0
	v_cmp_lt_u32_e64 s[16:17], v0, v84
	v_or_b32_e32 v15, 16, v0
	v_or_b32_e32 v16, 24, v0
	v_or_b32_e32 v18, 17, v0
	v_or_b32_e32 v19, 25, v0
	v_or_b32_e32 v21, 18, v0
	v_or_b32_e32 v22, 26, v0
	v_or_b32_e32 v24, 19, v0
	v_or_b32_e32 v0, 27, v0
	s_add_u32 s4, s54, 0xe000000
	v_lshl_add_u32 v3, v84, 1, v3
	v_mul_u32_u24_e32 v17, 0x88, v15
	v_mul_u32_u24_e32 v20, 0x88, v18
	v_mul_u32_u24_e32 v23, 0x88, v21
	v_mul_u32_u24_e32 v25, 0x88, v24
	v_cmp_lt_u32_e64 s[48:49], v0, v84
	v_lshlrev_b32_e32 v0, 8, v2
	v_add_u32_e32 v90, v5, v7
	s_addc_u32 s5, s55, 0
	s_mov_b32 s73, 0
	v_cmp_eq_u32_e64 s[12:13], 0, v1
	v_cmp_gt_u32_e64 s[14:15], 32, v1
	v_lshl_add_u64 v[68:69], s[68:69], 0, v[64:65]
	v_lshlrev_b32_e32 v85, 3, v1
	v_lshlrev_b32_e32 v86, 4, v1
	v_cmp_lt_u32_e64 s[18:19], v8, v84
	v_cmp_lt_u32_e64 s[20:21], v9, v84
	v_cmp_lt_u32_e64 s[22:23], v10, v84
	v_cmp_lt_u32_e64 s[24:25], v11, v84
	v_cmp_lt_u32_e64 s[26:27], v12, v84
	v_cmp_lt_u32_e64 s[28:29], v13, v84
	v_cmp_lt_u32_e64 s[30:31], v14, v84
	v_cmp_lt_u32_e64 s[34:35], v15, v84
	v_cmp_lt_u32_e64 s[36:37], v16, v84
	v_cmp_lt_u32_e64 s[38:39], v18, v84
	v_cmp_lt_u32_e64 s[40:41], v19, v84
	v_cmp_lt_u32_e64 s[42:43], v21, v84
	v_cmp_lt_u32_e64 s[44:45], v22, v84
	v_cmp_lt_u32_e64 s[46:47], v24, v84
	v_lshl_or_b32 v87, v2, 11, v1
	v_or3_b32 v88, v4, v0, 56
	s_lshl_b32 s6, s2, 7
	s_lshl_b32 s7, s50, 7
	v_or_b32_e32 v89, 0x3ec0, v1
	s_add_i32 s8, 0, 0x23014
	v_add_u32_e32 v91, 0x880, v90
	v_add_u32_e32 v92, 0xcc0, v90
	v_add_u32_e32 v93, 0x1100, v90
	v_add_u32_e32 v94, 0x1540, v90
	v_add_u32_e32 v95, 0x1980, v90
	v_add_u32_e32 v96, 0x1dc0, v90
	v_add_u32_e32 v97, v3, v6
	v_add_u32_e32 v98, v3, v17
	v_add_u32_e32 v99, v3, v20
	v_add_u32_e32 v100, v3, v23
	v_add_u32_e32 v101, v3, v25
	s_mov_b64 s[74:75], 0x800
	s_mov_b64 s[76:77], 0x400
	v_mbcnt_hi_u32_b32 v102, -1, v234
	s_mov_b32 s78, s2
	s_branch .LBB0_1738

; __device__ __forceinline__ unsigned xb_add(unsigned* p, unsigned v) { return __hip_atomic_fetch_add(p, v, __ATOMIC_RELAXED, __HIP_MEMORY_SCOPE_AGENT); }
; __device__ __forceinline__ void xcd_barrier(const XcdBarrier& b) {
;     asm volatile("s_waitcnt vmcnt(0) lgkmcnt(0)" ::: "memory");
;     __syncthreads();
;     if (threadIdx.x == 0) {
;         unsigned* bar = b.bar;
;         __builtin_amdgcn_s_waitcnt(0);
;         unsigned nloc = b.st[0], nx = b.st[1];
;         if (nloc == 0u) { xcd_barrier_complete(bar, b.x, nloc, nx); b.st[0] = nloc; b.st[1] = nx; }
;         const unsigned old = xb_add(&bar[XB_XSUB(b.x)], 1u);
.LBB0_1753:
	s_setprio 0
	s_waitcnt vmcnt(0) lgkmcnt(0)
	s_barrier
	s_mov_b64 s[10:11], exec
	v_readlane_b32 s4, v252, 0
	v_readlane_b32 s5, v252, 1
	s_and_b64 s[4:5], s[10:11], s[4:5]
	s_mov_b64 exec, s[4:5]
	s_cbranch_execz .LBB0_1805
	s_add_i32 s4, 0, 0x23000
	v_mov_b32_e32 v0, s4
	s_waitcnt vmcnt(0) expcnt(0) lgkmcnt(0)
	ds_read_b32 v2, v0
	s_add_i32 s4, 0, 0x23004
	v_mov_b32_e32 v0, s4
	ds_read_b32 v0, v0
	s_waitcnt lgkmcnt(1)
	v_cmp_ne_u32_e32 vcc, 0, v2
	s_cbranch_vccnz .LBB0_1769
	s_add_u32 s12, s54, 0x1000
	s_addc_u32 s13, s55, 0
	s_add_u32 s14, s54, 0x1100
	s_addc_u32 s15, s55, 0
	s_add_u32 s16, s54, 0x1200
	s_addc_u32 s17, s55, 0
	s_mul_i32 s4, s51, s96
	s_add_u32 s18, s54, 0x1300
	s_mul_i32 s4, s4, s50
	s_addc_u32 s19, s55, 0
	s_mov_b32 s5, 1
	v_mov_b32_e32 v16, 0
	s_branch .LBB0_1757
